# scan fast path: chunk loads issued 24 ahead of the recurrence
# speedup vs baseline: 1.0445x; 1.0445x over previous
; __device__ __forceinline__ int otid() { int t = threadIdx.x; asm volatile("" : "+v"(t)); return t; }
; __device__ __forceinline__ void hgrn_scan_phase(const Args& a) {
;     const int id = blockIdx.x * 512 + otid(), NT = gridDim.x * 512;
;     for (int it = id; it < 32 * 128 * 32; it += NT) {
;         const int bh = it >> 12, dv = (it >> 5) & 127, dkc = it & 31;
;         u32x2* st = (u32x2*)((bf16_t*)(a.ws + WS_H) + (size_t)bh * 32 * 16384 + dv * 128 + dkc * 4);
.LBB0_522:
	v_mov_b32_e32 v0, v178
	v_readlane_b32 s4, v245, 54
	s_nop 1
	v_add_u32_e32 v12, s4, v0
	s_mov_b32 s4, 0x20000
	v_cmp_gt_i32_e32 vcc, s4, v12
	s_and_saveexec_b64 s[40:41], vcc
	v_readlane_b32 s6, v245, 55
	s_cbranch_execz .LBB0_527
	s_nop 1
	s_cmp_eq_u32 s6, 0x20000
	s_cbranch_scc1 .Lscan_fast
	v_readlane_b32 s4, v244, 44
	s_mov_b64 s[42:43], 0
	s_nop 0
	v_lshl_add_u32 v13, v0, 2, s4

; __device__ __forceinline__ unsigned pk2(float lo, float hi) { f32x2_t v = {lo, hi}; bf16x2_t b = __builtin_convertvector(v, bf16x2_t); return __builtin_bit_cast(unsigned, b); }
; __device__ __forceinline__ float bflo(unsigned u) { return __uint_as_float(u << 16); }
; __device__ __forceinline__ float bfhi(unsigned u) { return __uint_as_float(u & 0xffff0000u); }
; __device__ __forceinline__ void hgrn_scan_phase(const Args& a) {
;     ...
;     for (int it = id; it < 32 * 128 * 32; it += NT) {
;         const int bh = it >> 12, dv = (it >> 5) & 127, dkc = it & 31;
;         u32x2* st = (u32x2*)((bf16_t*)(a.ws + WS_H) + (size_t)bh * 32 * 16384 + dv * 128 + dkc * 4);
;         const f32x4* dc = (const f32x4*)((const float*)(a.ws + WS_DECAY) + (size_t)bh * 32 * 128 + dkc * 4);
;         float r0 = 0.f, r1 = 0.f, r2 = 0.f, r3 = 0.f;
; #pragma unroll 8
;         for (int c = 0; c < 32; ++c) {
;             const u32x2 u = st[(size_t)c * 4096]; const f32x4 dd = dc[c * 32];
;             u32x2 o; o.x = pk2(r0, r1); o.y = pk2(r2, r3); st[(size_t)c * 4096] = o;
;             r0 = dd.x * r0 + bflo(u.x); r1 = dd.y * r1 + bfhi(u.x); r2 = dd.z * r2 + bflo(u.y); r3 = dd.w * r3 + bfhi(u.y);
;         }
.Lscan_fast:
	v_lshrrev_b32_e32 v222, 12, v12
	v_and_b32_e32 v220, 0xfff, v12
	v_and_b32_e32 v221, 31, v12
	v_lshlrev_b32_e32 v220, 3, v220
	v_lshlrev_b32_e32 v221, 4, v221
	v_lshl_or_b32 v220, v222, 20, v220
	v_lshl_or_b32 v221, v222, 14, v221
	s_add_u32 s10, s78, 0x1e00000
	s_addc_u32 s11, s79, 0
	s_mov_b32 s14, s10
	s_mov_b32 s15, s11
	s_add_u32 s8, s78, 0xf620000
	s_addc_u32 s9, s79, 0
	v_mov_b32_e32 v208, 0
	v_mov_b32_e32 v209, 0
	v_mov_b32_e32 v210, 0
	v_mov_b32_e32 v211, 0
	global_load_dwordx2 v[128:129], v220, s[10:11]
	s_add_u32 s10, s10, 0x8000
	s_addc_u32 s11, s11, 0
	global_load_dwordx4 v[12:15], v221, s[8:9]
	global_load_dwordx2 v[130:131], v220, s[10:11]
	s_add_u32 s10, s10, 0x8000
	s_addc_u32 s11, s11, 0
	global_load_dwordx4 v[16:19], v221, s[8:9] offset:512
	global_load_dwordx2 v[132:133], v220, s[10:11]
	s_add_u32 s10, s10, 0x8000
	s_addc_u32 s11, s11, 0
	global_load_dwordx4 v[20:23], v221, s[8:9] offset:1024
	global_load_dwordx2 v[134:135], v220, s[10:11]
	s_add_u32 s10, s10, 0x8000
	s_addc_u32 s11, s11, 0
	global_load_dwordx4 v[24:27], v221, s[8:9] offset:1536
	global_load_dwordx2 v[136:137], v220, s[10:11]
	s_add_u32 s10, s10, 0x8000
	s_addc_u32 s11, s11, 0
	global_load_dwordx4 v[28:31], v221, s[8:9] offset:2048
	global_load_dwordx2 v[138:139], v220, s[10:11]
	s_add_u32 s10, s10, 0x8000
	s_addc_u32 s11, s11, 0
	global_load_dwordx4 v[32:35], v221, s[8:9] offset:2560
	global_load_dwordx2 v[140:141], v220, s[10:11]
	s_add_u32 s10, s10, 0x8000
	s_addc_u32 s11, s11, 0
	global_load_dwordx4 v[36:39], v221, s[8:9] offset:3072
	global_load_dwordx2 v[142:143], v220, s[10:11]
	s_add_u32 s10, s10, 0x8000
	s_addc_u32 s11, s11, 0
	global_load_dwordx4 v[40:43], v221, s[8:9] offset:3584
	s_add_u32 s8, s8, 0x1000
	s_addc_u32 s9, s9, 0
	global_load_dwordx2 v[156:157], v220, s[10:11]
	s_add_u32 s10, s10, 0x8000
	s_addc_u32 s11, s11, 0
	global_load_dwordx4 v[44:47], v221, s[8:9]
	global_load_dwordx2 v[158:159], v220, s[10:11]
	s_add_u32 s10, s10, 0x8000
	s_addc_u32 s11, s11, 0
	global_load_dwordx4 v[48:51], v221, s[8:9] offset:512
	global_load_dwordx2 v[160:161], v220, s[10:11]
	s_add_u32 s10, s10, 0x8000
	s_addc_u32 s11, s11, 0
	global_load_dwordx4 v[52:55], v221, s[8:9] offset:1024
	global_load_dwordx2 v[162:163], v220, s[10:11]
	s_add_u32 s10, s10, 0x8000
	s_addc_u32 s11, s11, 0
	global_load_dwordx4 v[56:59], v221, s[8:9] offset:1536
	global_load_dwordx2 v[164:165], v220, s[10:11]
	s_add_u32 s10, s10, 0x8000
	s_addc_u32 s11, s11, 0
	global_load_dwordx4 v[60:63], v221, s[8:9] offset:2048
	global_load_dwordx2 v[166:167], v220, s[10:11]
	s_add_u32 s10, s10, 0x8000
	s_addc_u32 s11, s11, 0
	global_load_dwordx4 v[64:67], v221, s[8:9] offset:2560
	global_load_dwordx2 v[168:169], v220, s[10:11]
	s_add_u32 s10, s10, 0x8000
	s_addc_u32 s11, s11, 0
	global_load_dwordx4 v[68:71], v221, s[8:9] offset:3072
	global_load_dwordx2 v[170:171], v220, s[10:11]
	s_add_u32 s10, s10, 0x8000
	s_addc_u32 s11, s11, 0
	global_load_dwordx4 v[72:75], v221, s[8:9] offset:3584
	s_add_u32 s8, s8, 0x1000
	s_addc_u32 s9, s9, 0
	global_load_dwordx2 v[172:173], v220, s[10:11]
	s_add_u32 s10, s10, 0x8000
	s_addc_u32 s11, s11, 0
	global_load_dwordx4 v[76:79], v221, s[8:9]
	global_load_dwordx2 v[174:175], v220, s[10:11]
	s_add_u32 s10, s10, 0x8000
	s_addc_u32 s11, s11, 0
	global_load_dwordx4 v[84:87], v221, s[8:9] offset:512
	global_load_dwordx2 v[196:197], v220, s[10:11]
	s_add_u32 s10, s10, 0x8000
	s_addc_u32 s11, s11, 0
	global_load_dwordx4 v[88:91], v221, s[8:9] offset:1024
	global_load_dwordx2 v[198:199], v220, s[10:11]
	s_add_u32 s10, s10, 0x8000
	s_addc_u32 s11, s11, 0
	global_load_dwordx4 v[92:95], v221, s[8:9] offset:1536
	global_load_dwordx2 v[200:201], v220, s[10:11]
	s_add_u32 s10, s10, 0x8000
	s_addc_u32 s11, s11, 0
	global_load_dwordx4 v[100:103], v221, s[8:9] offset:2048
	global_load_dwordx2 v[202:203], v220, s[10:11]
	s_add_u32 s10, s10, 0x8000
	s_addc_u32 s11, s11, 0
	global_load_dwordx4 v[104:107], v221, s[8:9] offset:2560
	global_load_dwordx2 v[204:205], v220, s[10:11]
	s_add_u32 s10, s10, 0x8000
	s_addc_u32 s11, s11, 0
	global_load_dwordx4 v[108:111], v221, s[8:9] offset:3072
	global_load_dwordx2 v[206:207], v220, s[10:11]
	s_add_u32 s10, s10, 0x8000
	s_addc_u32 s11, s11, 0
	global_load_dwordx4 v[112:115], v221, s[8:9] offset:3584
	s_add_u32 s8, s8, 0x1000
	s_addc_u32 s9, s9, 0
	v_cvt_pk_bf16_f32 v216, v208, v209
	v_cvt_pk_bf16_f32 v217, v210, v211
	global_store_dwordx2 v220, v[216:217], s[14:15]
	s_add_u32 s14, s14, 0x8000
	s_addc_u32 s15, s15, 0
	s_waitcnt vmcnt(48)
	v_lshlrev_b32_e32 v212, 16, v128
	v_and_b32_e32 v213, 0xffff0000, v128
	v_lshlrev_b32_e32 v214, 16, v129
	v_and_b32_e32 v215, 0xffff0000, v129
	s_waitcnt vmcnt(47)
	v_pk_fma_f32 v[208:209], v[208:209], v[12:13], v[212:213]
	v_pk_fma_f32 v[210:211], v[210:211], v[14:15], v[214:215]
	global_load_dwordx2 v[128:129], v220, s[10:11]
	s_add_u32 s10, s10, 0x8000
	s_addc_u32 s11, s11, 0
	global_load_dwordx4 v[12:15], v221, s[8:9]
	v_cvt_pk_bf16_f32 v218, v208, v209
	v_cvt_pk_bf16_f32 v219, v210, v211
	global_store_dwordx2 v220, v[218:219], s[14:15]
	s_add_u32 s14, s14, 0x8000
	s_addc_u32 s15, s15, 0
	s_waitcnt vmcnt(49)
	v_lshlrev_b32_e32 v212, 16, v130
	v_and_b32_e32 v213, 0xffff0000, v130
	v_lshlrev_b32_e32 v214, 16, v131
	v_and_b32_e32 v215, 0xffff0000, v131
	s_waitcnt vmcnt(48)
	v_pk_fma_f32 v[208:209], v[208:209], v[16:17], v[212:213]
	v_pk_fma_f32 v[210:211], v[210:211], v[18:19], v[214:215]
	global_load_dwordx2 v[130:131], v220, s[10:11]
	s_add_u32 s10, s10, 0x8000
	s_addc_u32 s11, s11, 0
	global_load_dwordx4 v[16:19], v221, s[8:9] offset:512
	v_cvt_pk_bf16_f32 v216, v208, v209
	v_cvt_pk_bf16_f32 v217, v210, v211
	global_store_dwordx2 v220, v[216:217], s[14:15]
	s_add_u32 s14, s14, 0x8000
	s_addc_u32 s15, s15, 0
	s_waitcnt vmcnt(50)
; __device__ __forceinline__ unsigned pk2(float lo, float hi) { f32x2_t v = {lo, hi}; bf16x2_t b = __builtin_convertvector(v, bf16x2_t); return __builtin_bit_cast(unsigned, b); }
; __device__ __forceinline__ float bflo(unsigned u) { return __uint_as_float(u << 16); }
; __device__ __forceinline__ float bfhi(unsigned u) { return __uint_as_float(u & 0xffff0000u); }
; __device__ __forceinline__ void hgrn_scan_phase(const Args& a) {
;     ...
;         const f32x4* dc = (const f32x4*)((const float*)(a.ws + WS_DECAY) + (size_t)bh * 32 * 128 + dkc * 4);
;         float r0 = 0.f, r1 = 0.f, r2 = 0.f, r3 = 0.f;
; #pragma unroll 8
;         for (int c = 0; c < 32; ++c) {
;             const u32x2 u = st[(size_t)c * 4096]; const f32x4 dd = dc[c * 32];
;             u32x2 o; o.x = pk2(r0, r1); o.y = pk2(r2, r3); st[(size_t)c * 4096] = o;
;             r0 = dd.x * r0 + bflo(u.x); r1 = dd.y * r1 + bfhi(u.x); r2 = dd.z * r2 + bflo(u.y); r3 = dd.w * r3 + bfhi(u.y);
;         }
	v_lshlrev_b32_e32 v212, 16, v132
	v_and_b32_e32 v213, 0xffff0000, v132
	v_lshlrev_b32_e32 v214, 16, v133
	v_and_b32_e32 v215, 0xffff0000, v133
	s_waitcnt vmcnt(49)
	v_pk_fma_f32 v[208:209], v[208:209], v[20:21], v[212:213]
	v_pk_fma_f32 v[210:211], v[210:211], v[22:23], v[214:215]
	global_load_dwordx2 v[132:133], v220, s[10:11]
	s_add_u32 s10, s10, 0x8000
	s_addc_u32 s11, s11, 0
	global_load_dwordx4 v[20:23], v221, s[8:9] offset:1024
	v_cvt_pk_bf16_f32 v218, v208, v209
	v_cvt_pk_bf16_f32 v219, v210, v211
	global_store_dwordx2 v220, v[218:219], s[14:15]
	s_add_u32 s14, s14, 0x8000
	s_addc_u32 s15, s15, 0
	s_waitcnt vmcnt(51)
	v_lshlrev_b32_e32 v212, 16, v134
	v_and_b32_e32 v213, 0xffff0000, v134
	v_lshlrev_b32_e32 v214, 16, v135
	v_and_b32_e32 v215, 0xffff0000, v135
	s_waitcnt vmcnt(50)
	v_pk_fma_f32 v[208:209], v[208:209], v[24:25], v[212:213]
	v_pk_fma_f32 v[210:211], v[210:211], v[26:27], v[214:215]
	global_load_dwordx2 v[134:135], v220, s[10:11]
	s_add_u32 s10, s10, 0x8000
	s_addc_u32 s11, s11, 0
	global_load_dwordx4 v[24:27], v221, s[8:9] offset:1536
	v_cvt_pk_bf16_f32 v216, v208, v209
	v_cvt_pk_bf16_f32 v217, v210, v211
	global_store_dwordx2 v220, v[216:217], s[14:15]
	s_add_u32 s14, s14, 0x8000
	s_addc_u32 s15, s15, 0
	s_waitcnt vmcnt(52)
	v_lshlrev_b32_e32 v212, 16, v136
	v_and_b32_e32 v213, 0xffff0000, v136
	v_lshlrev_b32_e32 v214, 16, v137
	v_and_b32_e32 v215, 0xffff0000, v137
	s_waitcnt vmcnt(51)
	v_pk_fma_f32 v[208:209], v[208:209], v[28:29], v[212:213]
	v_pk_fma_f32 v[210:211], v[210:211], v[30:31], v[214:215]
	global_load_dwordx2 v[136:137], v220, s[10:11]
	s_add_u32 s10, s10, 0x8000
	s_addc_u32 s11, s11, 0
	global_load_dwordx4 v[28:31], v221, s[8:9] offset:2048
	v_cvt_pk_bf16_f32 v218, v208, v209
	v_cvt_pk_bf16_f32 v219, v210, v211
	global_store_dwordx2 v220, v[218:219], s[14:15]
	s_add_u32 s14, s14, 0x8000
	s_addc_u32 s15, s15, 0
	s_waitcnt vmcnt(53)
	v_lshlrev_b32_e32 v212, 16, v138
	v_and_b32_e32 v213, 0xffff0000, v138
	v_lshlrev_b32_e32 v214, 16, v139
	v_and_b32_e32 v215, 0xffff0000, v139
	s_waitcnt vmcnt(52)
	v_pk_fma_f32 v[208:209], v[208:209], v[32:33], v[212:213]
	v_pk_fma_f32 v[210:211], v[210:211], v[34:35], v[214:215]
	global_load_dwordx2 v[138:139], v220, s[10:11]
	s_add_u32 s10, s10, 0x8000
	s_addc_u32 s11, s11, 0
	global_load_dwordx4 v[32:35], v221, s[8:9] offset:2560
	v_cvt_pk_bf16_f32 v216, v208, v209
	v_cvt_pk_bf16_f32 v217, v210, v211
	global_store_dwordx2 v220, v[216:217], s[14:15]
	s_add_u32 s14, s14, 0x8000
	s_addc_u32 s15, s15, 0
	s_waitcnt vmcnt(54)
	v_lshlrev_b32_e32 v212, 16, v140
	v_and_b32_e32 v213, 0xffff0000, v140
	v_lshlrev_b32_e32 v214, 16, v141
	v_and_b32_e32 v215, 0xffff0000, v141
	s_waitcnt vmcnt(53)
	v_pk_fma_f32 v[208:209], v[208:209], v[36:37], v[212:213]
	v_pk_fma_f32 v[210:211], v[210:211], v[38:39], v[214:215]
	global_load_dwordx2 v[140:141], v220, s[10:11]
	s_add_u32 s10, s10, 0x8000
	s_addc_u32 s11, s11, 0
	global_load_dwordx4 v[36:39], v221, s[8:9] offset:3072
	v_cvt_pk_bf16_f32 v218, v208, v209
	v_cvt_pk_bf16_f32 v219, v210, v211
	global_store_dwordx2 v220, v[218:219], s[14:15]
	s_add_u32 s14, s14, 0x8000
	s_addc_u32 s15, s15, 0
	s_waitcnt vmcnt(55)
	v_lshlrev_b32_e32 v212, 16, v142
	v_and_b32_e32 v213, 0xffff0000, v142
	v_lshlrev_b32_e32 v214, 16, v143
	v_and_b32_e32 v215, 0xffff0000, v143
	s_waitcnt vmcnt(54)
	v_pk_fma_f32 v[208:209], v[208:209], v[40:41], v[212:213]
	v_pk_fma_f32 v[210:211], v[210:211], v[42:43], v[214:215]
	global_load_dwordx2 v[142:143], v220, s[10:11]
	s_add_u32 s10, s10, 0x8000
	s_addc_u32 s11, s11, 0
	global_load_dwordx4 v[40:43], v221, s[8:9] offset:3584
	s_add_u32 s8, s8, 0x1000
	s_addc_u32 s9, s9, 0
	v_cvt_pk_bf16_f32 v216, v208, v209
	v_cvt_pk_bf16_f32 v217, v210, v211
	global_store_dwordx2 v220, v[216:217], s[14:15]
	s_add_u32 s14, s14, 0x8000
	s_addc_u32 s15, s15, 0
	s_waitcnt vmcnt(56)
	v_lshlrev_b32_e32 v212, 16, v156
	v_and_b32_e32 v213, 0xffff0000, v156
	v_lshlrev_b32_e32 v214, 16, v157
	v_and_b32_e32 v215, 0xffff0000, v157
	s_waitcnt vmcnt(55)
	v_pk_fma_f32 v[208:209], v[208:209], v[44:45], v[212:213]
	v_pk_fma_f32 v[210:211], v[210:211], v[46:47], v[214:215]
	v_cvt_pk_bf16_f32 v218, v208, v209
	v_cvt_pk_bf16_f32 v219, v210, v211
	global_store_dwordx2 v220, v[218:219], s[14:15]
	s_add_u32 s14, s14, 0x8000
	s_addc_u32 s15, s15, 0
	s_waitcnt vmcnt(55)
	v_lshlrev_b32_e32 v212, 16, v158
	v_and_b32_e32 v213, 0xffff0000, v158
	v_lshlrev_b32_e32 v214, 16, v159
	v_and_b32_e32 v215, 0xffff0000, v159
	s_waitcnt vmcnt(54)
	v_pk_fma_f32 v[208:209], v[208:209], v[48:49], v[212:213]
	v_pk_fma_f32 v[210:211], v[210:211], v[50:51], v[214:215]
	v_cvt_pk_bf16_f32 v216, v208, v209
	v_cvt_pk_bf16_f32 v217, v210, v211
	global_store_dwordx2 v220, v[216:217], s[14:15]
	s_add_u32 s14, s14, 0x8000
	s_addc_u32 s15, s15, 0
	s_waitcnt vmcnt(54)
	v_lshlrev_b32_e32 v212, 16, v160
	v_and_b32_e32 v213, 0xffff0000, v160
	v_lshlrev_b32_e32 v214, 16, v161
	v_and_b32_e32 v215, 0xffff0000, v161
	s_waitcnt vmcnt(53)
	v_pk_fma_f32 v[208:209], v[208:209], v[52:53], v[212:213]
	v_pk_fma_f32 v[210:211], v[210:211], v[54:55], v[214:215]
	v_cvt_pk_bf16_f32 v218, v208, v209
	v_cvt_pk_bf16_f32 v219, v210, v211
	global_store_dwordx2 v220, v[218:219], s[14:15]
	s_add_u32 s14, s14, 0x8000
	s_addc_u32 s15, s15, 0
	s_waitcnt vmcnt(53)
	v_lshlrev_b32_e32 v212, 16, v162
	v_and_b32_e32 v213, 0xffff0000, v162
	v_lshlrev_b32_e32 v214, 16, v163
	v_and_b32_e32 v215, 0xffff0000, v163
	s_waitcnt vmcnt(52)
	v_pk_fma_f32 v[208:209], v[208:209], v[56:57], v[212:213]
	v_pk_fma_f32 v[210:211], v[210:211], v[58:59], v[214:215]
	v_cvt_pk_bf16_f32 v216, v208, v209
	v_cvt_pk_bf16_f32 v217, v210, v211
	global_store_dwordx2 v220, v[216:217], s[14:15]
	s_add_u32 s14, s14, 0x8000
	s_addc_u32 s15, s15, 0
	s_waitcnt vmcnt(52)
; __device__ __forceinline__ unsigned pk2(float lo, float hi) { f32x2_t v = {lo, hi}; bf16x2_t b = __builtin_convertvector(v, bf16x2_t); return __builtin_bit_cast(unsigned, b); }
; __device__ __forceinline__ float bflo(unsigned u) { return __uint_as_float(u << 16); }
; __device__ __forceinline__ float bfhi(unsigned u) { return __uint_as_float(u & 0xffff0000u); }
; __device__ __forceinline__ void hgrn_scan_phase(const Args& a) {
;     ...
;         const f32x4* dc = (const f32x4*)((const float*)(a.ws + WS_DECAY) + (size_t)bh * 32 * 128 + dkc * 4);
;         float r0 = 0.f, r1 = 0.f, r2 = 0.f, r3 = 0.f;
; #pragma unroll 8
;         for (int c = 0; c < 32; ++c) {
;             const u32x2 u = st[(size_t)c * 4096]; const f32x4 dd = dc[c * 32];
;             u32x2 o; o.x = pk2(r0, r1); o.y = pk2(r2, r3); st[(size_t)c * 4096] = o;
;             r0 = dd.x * r0 + bflo(u.x); r1 = dd.y * r1 + bfhi(u.x); r2 = dd.z * r2 + bflo(u.y); r3 = dd.w * r3 + bfhi(u.y);
;         }
	v_lshlrev_b32_e32 v212, 16, v164
	v_and_b32_e32 v213, 0xffff0000, v164
	v_lshlrev_b32_e32 v214, 16, v165
	v_and_b32_e32 v215, 0xffff0000, v165
	s_waitcnt vmcnt(51)
	v_pk_fma_f32 v[208:209], v[208:209], v[60:61], v[212:213]
	v_pk_fma_f32 v[210:211], v[210:211], v[62:63], v[214:215]
	v_cvt_pk_bf16_f32 v218, v208, v209
	v_cvt_pk_bf16_f32 v219, v210, v211
	global_store_dwordx2 v220, v[218:219], s[14:15]
	s_add_u32 s14, s14, 0x8000
	s_addc_u32 s15, s15, 0
	s_waitcnt vmcnt(51)
	v_lshlrev_b32_e32 v212, 16, v166
	v_and_b32_e32 v213, 0xffff0000, v166
	v_lshlrev_b32_e32 v214, 16, v167
	v_and_b32_e32 v215, 0xffff0000, v167
	s_waitcnt vmcnt(50)
	v_pk_fma_f32 v[208:209], v[208:209], v[64:65], v[212:213]
	v_pk_fma_f32 v[210:211], v[210:211], v[66:67], v[214:215]
	v_cvt_pk_bf16_f32 v216, v208, v209
	v_cvt_pk_bf16_f32 v217, v210, v211
	global_store_dwordx2 v220, v[216:217], s[14:15]
	s_add_u32 s14, s14, 0x8000
	s_addc_u32 s15, s15, 0
	s_waitcnt vmcnt(50)
	v_lshlrev_b32_e32 v212, 16, v168
	v_and_b32_e32 v213, 0xffff0000, v168
	v_lshlrev_b32_e32 v214, 16, v169
	v_and_b32_e32 v215, 0xffff0000, v169
	s_waitcnt vmcnt(49)
	v_pk_fma_f32 v[208:209], v[208:209], v[68:69], v[212:213]
	v_pk_fma_f32 v[210:211], v[210:211], v[70:71], v[214:215]
	v_cvt_pk_bf16_f32 v218, v208, v209
	v_cvt_pk_bf16_f32 v219, v210, v211
	global_store_dwordx2 v220, v[218:219], s[14:15]
	s_add_u32 s14, s14, 0x8000
	s_addc_u32 s15, s15, 0
	s_waitcnt vmcnt(49)
	v_lshlrev_b32_e32 v212, 16, v170
	v_and_b32_e32 v213, 0xffff0000, v170
	v_lshlrev_b32_e32 v214, 16, v171
	v_and_b32_e32 v215, 0xffff0000, v171
	s_waitcnt vmcnt(48)
	v_pk_fma_f32 v[208:209], v[208:209], v[72:73], v[212:213]
	v_pk_fma_f32 v[210:211], v[210:211], v[74:75], v[214:215]
	v_cvt_pk_bf16_f32 v216, v208, v209
	v_cvt_pk_bf16_f32 v217, v210, v211
	global_store_dwordx2 v220, v[216:217], s[14:15]
	s_add_u32 s14, s14, 0x8000
	s_addc_u32 s15, s15, 0
	s_waitcnt vmcnt(48)
	v_lshlrev_b32_e32 v212, 16, v172
	v_and_b32_e32 v213, 0xffff0000, v172
	v_lshlrev_b32_e32 v214, 16, v173
	v_and_b32_e32 v215, 0xffff0000, v173
	s_waitcnt vmcnt(47)
	v_pk_fma_f32 v[208:209], v[208:209], v[76:77], v[212:213]
	v_pk_fma_f32 v[210:211], v[210:211], v[78:79], v[214:215]
	v_cvt_pk_bf16_f32 v218, v208, v209
	v_cvt_pk_bf16_f32 v219, v210, v211
	global_store_dwordx2 v220, v[218:219], s[14:15]
	s_add_u32 s14, s14, 0x8000
	s_addc_u32 s15, s15, 0
	s_waitcnt vmcnt(47)
	v_lshlrev_b32_e32 v212, 16, v174
	v_and_b32_e32 v213, 0xffff0000, v174
	v_lshlrev_b32_e32 v214, 16, v175
	v_and_b32_e32 v215, 0xffff0000, v175
	s_waitcnt vmcnt(46)
	v_pk_fma_f32 v[208:209], v[208:209], v[84:85], v[212:213]
	v_pk_fma_f32 v[210:211], v[210:211], v[86:87], v[214:215]
	v_cvt_pk_bf16_f32 v216, v208, v209
	v_cvt_pk_bf16_f32 v217, v210, v211
	global_store_dwordx2 v220, v[216:217], s[14:15]
	s_add_u32 s14, s14, 0x8000
	s_addc_u32 s15, s15, 0
	s_waitcnt vmcnt(46)
	v_lshlrev_b32_e32 v212, 16, v196
	v_and_b32_e32 v213, 0xffff0000, v196
	v_lshlrev_b32_e32 v214, 16, v197
	v_and_b32_e32 v215, 0xffff0000, v197
	s_waitcnt vmcnt(45)
	v_pk_fma_f32 v[208:209], v[208:209], v[88:89], v[212:213]
	v_pk_fma_f32 v[210:211], v[210:211], v[90:91], v[214:215]
	v_cvt_pk_bf16_f32 v218, v208, v209
	v_cvt_pk_bf16_f32 v219, v210, v211
	global_store_dwordx2 v220, v[218:219], s[14:15]
	s_add_u32 s14, s14, 0x8000
	s_addc_u32 s15, s15, 0
	s_waitcnt vmcnt(45)
	v_lshlrev_b32_e32 v212, 16, v198
	v_and_b32_e32 v213, 0xffff0000, v198
	v_lshlrev_b32_e32 v214, 16, v199
	v_and_b32_e32 v215, 0xffff0000, v199
	s_waitcnt vmcnt(44)
	v_pk_fma_f32 v[208:209], v[208:209], v[92:93], v[212:213]
	v_pk_fma_f32 v[210:211], v[210:211], v[94:95], v[214:215]
	v_cvt_pk_bf16_f32 v216, v208, v209
	v_cvt_pk_bf16_f32 v217, v210, v211
	global_store_dwordx2 v220, v[216:217], s[14:15]
	s_add_u32 s14, s14, 0x8000
	s_addc_u32 s15, s15, 0
	s_waitcnt vmcnt(44)
	v_lshlrev_b32_e32 v212, 16, v200
	v_and_b32_e32 v213, 0xffff0000, v200
	v_lshlrev_b32_e32 v214, 16, v201
	v_and_b32_e32 v215, 0xffff0000, v201
	s_waitcnt vmcnt(43)
	v_pk_fma_f32 v[208:209], v[208:209], v[100:101], v[212:213]
	v_pk_fma_f32 v[210:211], v[210:211], v[102:103], v[214:215]
	v_cvt_pk_bf16_f32 v218, v208, v209
	v_cvt_pk_bf16_f32 v219, v210, v211
	global_store_dwordx2 v220, v[218:219], s[14:15]
	s_add_u32 s14, s14, 0x8000
	s_addc_u32 s15, s15, 0
	s_waitcnt vmcnt(43)
	v_lshlrev_b32_e32 v212, 16, v202
	v_and_b32_e32 v213, 0xffff0000, v202
	v_lshlrev_b32_e32 v214, 16, v203
	v_and_b32_e32 v215, 0xffff0000, v203
	s_waitcnt vmcnt(42)
	v_pk_fma_f32 v[208:209], v[208:209], v[104:105], v[212:213]
	v_pk_fma_f32 v[210:211], v[210:211], v[106:107], v[214:215]
	v_cvt_pk_bf16_f32 v216, v208, v209
	v_cvt_pk_bf16_f32 v217, v210, v211
	global_store_dwordx2 v220, v[216:217], s[14:15]
	s_add_u32 s14, s14, 0x8000
	s_addc_u32 s15, s15, 0
	s_waitcnt vmcnt(42)
; __device__ __forceinline__ unsigned pk2(float lo, float hi) { f32x2_t v = {lo, hi}; bf16x2_t b = __builtin_convertvector(v, bf16x2_t); return __builtin_bit_cast(unsigned, b); }
; __device__ __forceinline__ float bflo(unsigned u) { return __uint_as_float(u << 16); }
; __device__ __forceinline__ float bfhi(unsigned u) { return __uint_as_float(u & 0xffff0000u); }
; __device__ __forceinline__ void hgrn_scan_phase(const Args& a) {
;     ...
;         const f32x4* dc = (const f32x4*)((const float*)(a.ws + WS_DECAY) + (size_t)bh * 32 * 128 + dkc * 4);
;         float r0 = 0.f, r1 = 0.f, r2 = 0.f, r3 = 0.f;
; #pragma unroll 8
;         for (int c = 0; c < 32; ++c) {
;             const u32x2 u = st[(size_t)c * 4096]; const f32x4 dd = dc[c * 32];
;             u32x2 o; o.x = pk2(r0, r1); o.y = pk2(r2, r3); st[(size_t)c * 4096] = o;
;             r0 = dd.x * r0 + bflo(u.x); r1 = dd.y * r1 + bfhi(u.x); r2 = dd.z * r2 + bflo(u.y); r3 = dd.w * r3 + bfhi(u.y);
;         }
	v_lshlrev_b32_e32 v212, 16, v204
	v_and_b32_e32 v213, 0xffff0000, v204
	v_lshlrev_b32_e32 v214, 16, v205
	v_and_b32_e32 v215, 0xffff0000, v205
	s_waitcnt vmcnt(41)
	v_pk_fma_f32 v[208:209], v[208:209], v[108:109], v[212:213]
	v_pk_fma_f32 v[210:211], v[210:211], v[110:111], v[214:215]
	v_cvt_pk_bf16_f32 v218, v208, v209
	v_cvt_pk_bf16_f32 v219, v210, v211
	global_store_dwordx2 v220, v[218:219], s[14:15]
	s_add_u32 s14, s14, 0x8000
	s_addc_u32 s15, s15, 0
	s_waitcnt vmcnt(41)
	v_lshlrev_b32_e32 v212, 16, v206
	v_and_b32_e32 v213, 0xffff0000, v206
	v_lshlrev_b32_e32 v214, 16, v207
	v_and_b32_e32 v215, 0xffff0000, v207
	s_waitcnt vmcnt(40)
	v_pk_fma_f32 v[208:209], v[208:209], v[112:113], v[212:213]
	v_pk_fma_f32 v[210:211], v[210:211], v[114:115], v[214:215]
	v_cvt_pk_bf16_f32 v216, v208, v209
	v_cvt_pk_bf16_f32 v217, v210, v211
	global_store_dwordx2 v220, v[216:217], s[14:15]
	s_add_u32 s14, s14, 0x8000
	s_addc_u32 s15, s15, 0
	s_waitcnt vmcnt(39)
	v_lshlrev_b32_e32 v212, 16, v128
	v_and_b32_e32 v213, 0xffff0000, v128
	v_lshlrev_b32_e32 v214, 16, v129
	v_and_b32_e32 v215, 0xffff0000, v129
	s_waitcnt vmcnt(38)
	v_pk_fma_f32 v[208:209], v[208:209], v[12:13], v[212:213]
	v_pk_fma_f32 v[210:211], v[210:211], v[14:15], v[214:215]
	v_cvt_pk_bf16_f32 v218, v208, v209
	v_cvt_pk_bf16_f32 v219, v210, v211
	global_store_dwordx2 v220, v[218:219], s[14:15]
	s_add_u32 s14, s14, 0x8000
	s_addc_u32 s15, s15, 0
	s_waitcnt vmcnt(37)
	v_lshlrev_b32_e32 v212, 16, v130
	v_and_b32_e32 v213, 0xffff0000, v130
	v_lshlrev_b32_e32 v214, 16, v131
	v_and_b32_e32 v215, 0xffff0000, v131
	s_waitcnt vmcnt(36)
	v_pk_fma_f32 v[208:209], v[208:209], v[16:17], v[212:213]
	v_pk_fma_f32 v[210:211], v[210:211], v[18:19], v[214:215]
	v_cvt_pk_bf16_f32 v216, v208, v209
	v_cvt_pk_bf16_f32 v217, v210, v211
	global_store_dwordx2 v220, v[216:217], s[14:15]
	s_add_u32 s14, s14, 0x8000
	s_addc_u32 s15, s15, 0
	s_waitcnt vmcnt(35)
	v_lshlrev_b32_e32 v212, 16, v132
	v_and_b32_e32 v213, 0xffff0000, v132
	v_lshlrev_b32_e32 v214, 16, v133
	v_and_b32_e32 v215, 0xffff0000, v133
	s_waitcnt vmcnt(34)
	v_pk_fma_f32 v[208:209], v[208:209], v[20:21], v[212:213]
	v_pk_fma_f32 v[210:211], v[210:211], v[22:23], v[214:215]
	v_cvt_pk_bf16_f32 v218, v208, v209
	v_cvt_pk_bf16_f32 v219, v210, v211
	global_store_dwordx2 v220, v[218:219], s[14:15]
	s_add_u32 s14, s14, 0x8000
	s_addc_u32 s15, s15, 0
	s_waitcnt vmcnt(33)
	v_lshlrev_b32_e32 v212, 16, v134
	v_and_b32_e32 v213, 0xffff0000, v134
	v_lshlrev_b32_e32 v214, 16, v135
	v_and_b32_e32 v215, 0xffff0000, v135
	s_waitcnt vmcnt(32)
	v_pk_fma_f32 v[208:209], v[208:209], v[24:25], v[212:213]
	v_pk_fma_f32 v[210:211], v[210:211], v[26:27], v[214:215]
	v_cvt_pk_bf16_f32 v216, v208, v209
	v_cvt_pk_bf16_f32 v217, v210, v211
	global_store_dwordx2 v220, v[216:217], s[14:15]
	s_add_u32 s14, s14, 0x8000
	s_addc_u32 s15, s15, 0
	s_waitcnt vmcnt(31)
	v_lshlrev_b32_e32 v212, 16, v136
	v_and_b32_e32 v213, 0xffff0000, v136
	v_lshlrev_b32_e32 v214, 16, v137
	v_and_b32_e32 v215, 0xffff0000, v137
	s_waitcnt vmcnt(30)
	v_pk_fma_f32 v[208:209], v[208:209], v[28:29], v[212:213]
	v_pk_fma_f32 v[210:211], v[210:211], v[30:31], v[214:215]
	v_cvt_pk_bf16_f32 v218, v208, v209
	v_cvt_pk_bf16_f32 v219, v210, v211
	global_store_dwordx2 v220, v[218:219], s[14:15]
	s_add_u32 s14, s14, 0x8000
	s_addc_u32 s15, s15, 0
	s_waitcnt vmcnt(29)
	v_lshlrev_b32_e32 v212, 16, v138
	v_and_b32_e32 v213, 0xffff0000, v138
	v_lshlrev_b32_e32 v214, 16, v139
	v_and_b32_e32 v215, 0xffff0000, v139
	s_waitcnt vmcnt(28)
	v_pk_fma_f32 v[208:209], v[208:209], v[32:33], v[212:213]
	v_pk_fma_f32 v[210:211], v[210:211], v[34:35], v[214:215]
	v_cvt_pk_bf16_f32 v216, v208, v209
	v_cvt_pk_bf16_f32 v217, v210, v211
	global_store_dwordx2 v220, v[216:217], s[14:15]
	s_add_u32 s14, s14, 0x8000
	s_addc_u32 s15, s15, 0
	s_waitcnt vmcnt(27)
	v_lshlrev_b32_e32 v212, 16, v140
	v_and_b32_e32 v213, 0xffff0000, v140
	v_lshlrev_b32_e32 v214, 16, v141
	v_and_b32_e32 v215, 0xffff0000, v141
	s_waitcnt vmcnt(26)
	v_pk_fma_f32 v[208:209], v[208:209], v[36:37], v[212:213]
	v_pk_fma_f32 v[210:211], v[210:211], v[38:39], v[214:215]
	v_cvt_pk_bf16_f32 v218, v208, v209
	v_cvt_pk_bf16_f32 v219, v210, v211
	global_store_dwordx2 v220, v[218:219], s[14:15]
	s_add_u32 s14, s14, 0x8000
	s_addc_u32 s15, s15, 0
	s_waitcnt vmcnt(25)
	v_lshlrev_b32_e32 v212, 16, v142
	v_and_b32_e32 v213, 0xffff0000, v142
	v_lshlrev_b32_e32 v214, 16, v143
	v_and_b32_e32 v215, 0xffff0000, v143
	s_waitcnt vmcnt(24)
	v_pk_fma_f32 v[208:209], v[208:209], v[40:41], v[212:213]
	v_pk_fma_f32 v[210:211], v[210:211], v[42:43], v[214:215]
	s_branch .LBB0_527
